# P3 prompt scan: the two column-half workgroups of a (batch, head) placed on the same XCD (workgroup ids 8 apart) so shared q/k loads hit L2, on top of v9
# baseline (speedup 1.0000x reference)
.LBB0_1198:
	s_and_b64 vcc, exec, s[2:3]
	s_cbranch_vccz .LBB0_1229
	s_and_b32 s3, s85, 7
	s_lshl_b32 s3, s3, 1
	s_bfe_u32 s2, s85, 0x10003
	s_or_b32 s3, s3, s2
	s_and_b32 s2, s85, 0x70
	s_or_b32 s3, s3, s2
	s_ashr_i32 s8, s3, 4
	s_lshl_b32 s2, s3, 6
	s_bfe_u32 s16, s3, 0x30001
	s_bfe_u32 s12, s3, 0x20001
	s_lshl_b32 s10, s8, 11
	s_and_b32 s22, s2, 64
	s_lshr_b32 s100, s22, 6
	v_bfe_u32 v240, v1, 3, 1
	v_cmp_eq_u32_e64 s[100:101], v240, s100
	s_cmp_lt_u32 s16, 4
	s_cselect_b64 s[2:3], -1, 0
	s_lshl_b32 s4, s8, 2
	s_or_b32 s4, s4, s12
	s_ashr_i32 s5, s4, 31
	s_mov_b32 s9, 0x4400000
	s_and_b64 s[6:7], s[2:3], exec
	v_readlane_b32 s24, v255, 0
	s_cselect_b32 s6, s9, 0x4500000
	v_readlane_b32 s26, v255, 2
	v_readlane_b32 s27, v255, 3
	s_add_u32 s9, s26, s6
	s_addc_u32 s11, s27, 0
	s_and_b64 s[6:7], s[2:3], exec
	s_cselect_b32 s6, 15, 16
	s_lshl_b64 s[4:5], s[4:5], s6
	s_add_u32 s4, s9, s4
	s_addc_u32 s5, s11, s5
	s_ashr_i32 s11, s10, 31
	s_mul_i32 s6, s8, 0xe00000
	s_mul_hi_i32 s7, s10, 0x1c00
	s_add_u32 s6, s20, s6
	s_addc_u32 s7, s21, s7
	s_lshl_b32 s13, s12, 6
	s_lshl_b32 s12, s12, 7
	s_bitset1_b32 s13, 8
	s_bitset1_b32 s12, 11
	s_and_b64 s[2:3], s[2:3], exec
	s_cselect_b32 s2, s13, s12
	s_lshl_b32 s2, s2, 1
	s_add_u32 s14, s6, s2
	s_addc_u32 s15, s7, 0
	s_lshl_b32 s2, s8, 9
	s_or_b32 s2, s2, s16
	s_ashr_i32 s3, s2, 31
	s_lshl_b64 s[2:3], s[2:3], 9
	s_add_u32 s12, s62, s2
	s_addc_u32 s13, s63, s3
	s_lshl_b32 s8, s86, 4
	s_cmpk_lt_u32 s87, 0x100
	s_cselect_b64 s[6:7], -1, 0
	s_and_b64 s[2:3], s[6:7], exec
	s_cselect_b32 s23, s8, 0
	s_add_i32 s2, s23, s22
	v_and_b32_e32 v115, 15, v1
	v_lshrrev_b32_e32 v117, 4, v1
	s_lshl_b32 s8, s16, 7
	v_lshrrev_b32_e32 v112, 4, v254
	v_or_b32_e32 v98, s2, v115
	v_min_u32_e32 v2, 31, v117
	s_mov_b32 s17, 0
	s_movk_i32 s9, 0x1c00
	s_cmp_gt_u32 s16, 3
	s_mov_b64 s[2:3], -1
	v_lshlrev_b32_e32 v100, 4, v115
	v_or_b32_e32 v118, s10, v2
	v_lshl_add_u32 v113, v112, 3, 0
	v_lshl_add_u32 v114, v98, 1, 0
	v_or_b32_e32 v116, 48, v254
	v_readlane_b32 s25, v255, 1
	s_cbranch_scc0 .LBB0_1214
	v_bfe_u32 v10, v1, 4, 5
	s_lshl_b32 s18, s8, 1
	v_or_b32_e32 v4, s10, v10
	v_mov_b64_e32 v[2:3], s[20:21]
	v_mad_i64_i32 v[4:5], s[2:3], v4, s9, v[2:3]
	s_or_b32 s16, s18, 0xc00
	v_lshl_add_u64 v[4:5], v[4:5], 0, s[16:17]
	v_mov_b32_e32 v101, 0
	v_lshl_add_u64 v[102:103], v[4:5], 0, v[100:101]
	v_mul_u32_u24_e32 v4, 0xe00, v10
	v_lshlrev_b32_e32 v4, 1, v4
	v_mov_b32_e32 v5, v101
	v_mad_i64_i32 v[2:3], s[2:3], v118, s9, v[2:3]
	s_or_b32 s16, s18, 0x1400
	v_and_b32_e32 v6, 31, v1
	v_lshl_add_u64 v[4:5], s[14:15], 0, v[4:5]
	v_lshl_add_u64 v[2:3], v[2:3], 0, s[16:17]
	v_lshl_add_u64 v[104:105], v[4:5], 0, v[100:101]
	v_lshlrev_b32_e32 v4, 4, v6
	v_lshl_add_u64 v[106:107], v[2:3], 0, v[100:101]
	global_load_dwordx4 v[18:21], v[102:103], off
	global_load_dwordx4 v[22:25], v[104:105], off
	global_load_dwordx4 v[26:29], v4, s[12:13]
	global_load_dwordx4 v[30:33], v[106:107], off
	v_mov_b32_e32 v5, v101
	s_movk_i32 s2, 0x2000
	v_lshl_add_u64 v[108:109], s[12:13], 0, v[4:5]
	v_add_co_u32_e32 v2, vcc, s2, v108
	s_mov_b32 s9, 0x38000
	s_nop 0
	v_addc_co_u32_e32 v3, vcc, 0, v109, vcc
	v_add_co_u32_e32 v6, vcc, s9, v102
	global_load_dwordx4 v[42:45], v[2:3], off offset:-4096
	s_nop 0
	v_addc_co_u32_e32 v7, vcc, 0, v103, vcc
	v_add_co_u32_e32 v8, vcc, s9, v104
	s_movk_i32 s2, 0x110
	s_nop 0
	v_addc_co_u32_e32 v9, vcc, 0, v105, vcc
	global_load_dwordx4 v[54:57], v[6:7], off
	global_load_dwordx4 v[58:61], v[8:9], off
	v_add_co_u32_e32 v6, vcc, s9, v106
	v_bfe_u32 v5, v1, 2, 7
	s_nop 0
	v_addc_co_u32_e32 v7, vcc, 0, v107, vcc
	global_load_dwordx4 v[62:65], v[6:7], off
	s_movk_i32 s3, 0x50
	v_lshlrev_b32_e32 v6, 4, v1
	s_mov_b32 s16, 0x70000
	v_mad_u32_u24 v7, v10, s2, 0
	v_mad_u32_u24 v5, v5, s3, 0
	v_and_b32_e32 v6, 48, v6
	v_mad_u32_u24 v8, v117, s2, 0
	v_add_u32_e32 v99, v7, v100
	v_add_u32_e32 v119, v5, v6
	v_add_u32_e32 v121, v8, v100
	global_load_dwordx4 v[6:9], v[2:3], off
	v_add_co_u32_e32 v2, vcc, s16, v102
	s_mov_b32 s18, 0xe0000
	s_nop 0
	v_addc_co_u32_e32 v3, vcc, 0, v103, vcc
	v_add_co_u32_e32 v10, vcc, s16, v104
	v_add_u32_e32 v120, 0, v4
	s_nop 0
	v_addc_co_u32_e32 v11, vcc, 0, v105, vcc
	v_add_co_u32_e32 v14, vcc, s18, v106
	global_load_dwordx4 v[2:5], v[2:3], off
	s_nop 0
	global_load_dwordx4 v[10:13], v[10:11], off
	v_addc_co_u32_e32 v15, vcc, 0, v107, vcc
	global_load_dwordx4 v[14:17], v[14:15], off
	s_mov_b32 s2, 0xa8000
	s_movk_i32 s3, 0x4000
	s_movk_i32 s24, 0x1000
	s_mov_b32 s25, 0x8000
	s_mov_b32 s26, 0x9000
	s_mov_b32 s27, 0x10000
	s_mov_b32 s28, 0x11000
	s_mov_b32 s29, 0x18000
	s_mov_b32 s30, 0x19000
	s_mov_b32 s31, 0x20000
	s_mov_b32 s33, 0x21000
	s_mov_b32 s34, 0x28000
	s_waitcnt vmcnt(0)
	ds_write_b128 v99, v[18:21]
	ds_write_b128 v119, v[22:25] offset:8704
	ds_write_b128 v120, v[26:29] offset:18944
	ds_write_b128 v121, v[30:33] offset:19456
	v_add_co_u32_e32 v18, vcc, s16, v106
	s_mov_b32 s35, 0x29000
	s_nop 0
	v_addc_co_u32_e32 v19, vcc, 0, v107, vcc
	v_add_co_u32_e32 v20, vcc, s2, v102
	s_mov_b32 s36, 0x30000
	s_nop 0
	v_addc_co_u32_e32 v21, vcc, 0, v103, vcc
	v_add_co_u32_e32 v26, vcc, s2, v104
	global_load_dwordx4 v[22:25], v[18:19], off
	s_nop 0
	global_load_dwordx4 v[18:21], v[20:21], off
	v_addc_co_u32_e32 v27, vcc, 0, v105, vcc
	v_add_co_u32_e32 v50, vcc, s3, v108
	s_mov_b32 s37, 0x31000
	s_nop 0
	v_addc_co_u32_e32 v51, vcc, 0, v109, vcc
	v_add_co_u32_e32 v30, vcc, s2, v106
	s_lshl_b64 s[2:3], s[10:11], 11
	s_nop 0
	v_addc_co_u32_e32 v31, vcc, 0, v107, vcc
	global_load_dwordx4 v[26:29], v[26:27], off
	s_nop 0
	global_load_dwordx4 v[38:41], v[30:31], off
	v_add_co_u32_e32 v30, vcc, s18, v102
	s_mov_b32 s38, 0x39000
	s_nop 0
	v_addc_co_u32_e32 v31, vcc, 0, v103, vcc
	v_add_co_u32_e32 v34, vcc, s18, v104
	s_mov_b64 s[18:19], 0x40000
	s_nop 0
	v_addc_co_u32_e32 v35, vcc, 0, v105, vcc
	global_load_dwordx4 v[30:33], v[30:31], off
	s_nop 0
	global_load_dwordx4 v[34:37], v[34:35], off
	s_nop 0
	global_load_dwordx4 v[46:49], v[50:51], off offset:-4096
	s_nop 0
	global_load_dwordx4 v[50:53], v[50:51], off
	ds_write_b128 v99, v[54:57] offset:28160
	ds_write_b128 v119, v[58:61] offset:36864
	ds_write_b128 v120, v[42:45] offset:47104
	ds_write_b128 v121, v[62:65] offset:47616
	v_and_b32_e32 v42, 48, v1
	v_or_b32_e32 v43, 0x70, v254
	v_add_u32_e32 v122, 0, v42
	v_mul_u32_u24_e32 v58, 0x50, v43
	v_lshlrev_b32_e32 v42, 9, v42
	v_mov_b32_e32 v43, v101
	v_lshl_add_u64 v[42:43], v[42:43], 0, s[2:3]
	s_add_i32 s2, s23, s8
	s_add_i32 s2, s2, s22
	v_add_u32_e32 v44, s2, v115
	v_mov_b32_e32 v45, v101
	s_waitcnt lgkmcnt(0)
	s_barrier
	v_lshl_add_u64 v[42:43], v[44:45], 1, v[42:43]
	v_mul_u32_u24_e32 v54, 0x110, v115
	v_mul_u32_u24_e32 v55, 0x880, v112
	v_mul_u32_u24_e32 v56, 0x50, v115
	v_mul_u32_u24_e32 v57, 0x50, v116
	v_lshl_add_u64 v[42:43], s[46:47], 0, v[42:43]
	s_mov_b64 s[2:3], 0x4f00000
	v_lshl_add_u64 v[110:111], v[42:43], 0, s[2:3]
	v_add_u32_e32 v123, v113, v54
	v_add_u32_e32 v124, v114, v55
	v_add_u32_e32 v125, v122, v56
	v_add_u32_e32 v126, v122, v57
	v_add_u32_e32 v127, v122, v58
	s_mov_b32 s39, 0
	v_mov_b32_e32 v70, v101
	v_mov_b32_e32 v71, v101
	v_mov_b32_e32 v72, v101
	v_mov_b32_e32 v73, v101
	v_mov_b32_e32 v66, v101
	v_mov_b32_e32 v67, v101
	v_mov_b32_e32 v68, v101
	v_mov_b32_e32 v69, v101
	v_mov_b32_e32 v74, v101
	v_mov_b32_e32 v75, v101
	v_mov_b32_e32 v76, v101
	v_mov_b32_e32 v77, v101
	v_mov_b32_e32 v78, v101
	v_mov_b32_e32 v79, v101
	v_mov_b32_e32 v80, v101
	v_mov_b32_e32 v81, v101
	v_mov_b32_e32 v62, v101
	v_mov_b32_e32 v63, v101
	v_mov_b32_e32 v64, v101
	v_mov_b32_e32 v65, v101
	v_mov_b32_e32 v54, v101
	v_mov_b32_e32 v55, v101
	v_mov_b32_e32 v56, v101
	v_mov_b32_e32 v57, v101
	v_mov_b32_e32 v42, v101
	v_mov_b32_e32 v43, v101
	v_mov_b32_e32 v44, v101
	v_mov_b32_e32 v58, v101
	v_mov_b32_e32 v59, v101
	v_mov_b32_e32 v60, v101
	v_mov_b32_e32 v61, v101
